# grid barrier: non-leader workgroups poll the cross-XCD release generation directly instead of the per-XCD generation (one hop fewer); plus attention staging edits
# speedup vs baseline: 1.0044x; 1.0044x over previous
.LBB0_130:
	s_or_b64 exec, exec, s[26:27]
	v_cvt_f32_u32_e32 v5, v3
	s_waitcnt vmcnt(0)
	v_readfirstlane_b32 s0, v4
	v_sub_u32_e32 v4, 0, v3
	v_rcp_iflag_f32_e32 v5, v5
	v_add_u32_e32 v6, s0, v0
	v_mul_f32_e32 v5, 0x4f7ffffe, v5
	v_cvt_u32_f32_e32 v5, v5
	v_mul_lo_u32 v0, v4, v5
	v_mul_hi_u32 v0, v5, v0
	v_add_u32_e32 v0, v5, v0
	v_mul_hi_u32 v0, v6, v0
	v_mul_lo_u32 v4, v0, v3
	v_sub_u32_e32 v4, v6, v4
	v_add_u32_e32 v5, 1, v0
	v_cmp_ge_u32_e32 vcc, v4, v3
	s_nop 1
	v_cndmask_b32_e32 v0, v0, v5, vcc
	v_sub_u32_e32 v5, v4, v3
	v_cndmask_b32_e32 v4, v4, v5, vcc
	v_add_u32_e32 v5, 1, v0
	v_cmp_ge_u32_e32 vcc, v4, v3
	v_add_u32_e32 v4, 1, v6
	s_nop 0
	v_cndmask_b32_e32 v0, v0, v5, vcc
	v_mul_lo_u32 v5, v3, v0
	v_add_u32_e32 v3, v5, v3
	v_cmp_ne_u32_e32 vcc, v4, v3
	s_and_saveexec_b64 s[14:15], vcc
	s_xor_b64 s[26:27], exec, s[14:15]
	s_cbranch_execz .LBB0_144
	v_readlane_b32 s14, v251, 52
	v_readlane_b32 s15, v251, 53
	s_waitcnt lgkmcnt(0)
	s_nop 3
	global_load_dword v2, v1, s[14:15] sc1
	s_waitcnt vmcnt(0)
	v_cmp_eq_u32_e32 vcc, v2, v0
	s_and_saveexec_b64 s[28:29], vcc
	s_cbranch_execz .LBB0_143
	s_mov_b32 s0, 1
	s_mov_b64 s[30:31], 0
	s_branch .LBB0_134
